# NSA select/window attention near-diagonal tiles: per-head bias table extended over negative and out-of-window distances (masked entries), lookups by immediate offset, no per-element clamp/compare/sele
# speedup vs baseline: 1.0392x; 1.0092x over previous
; template <int MODE>
; __device__ __forceinline__ void attn_pass(LAS unsigned char* lds, const bf16_t* base, int gk, int q0, const float* relb_b, const unsigned* selrow, f32x4 (&o)[2][4]) {
;     ...
;     bf16x8 qf[2][2];
; #pragma unroll
;     for (int qt = 0; qt < 2; ++qt)
; #pragma unroll
;         for (int ks = 0; ks < 2; ++ks) qf[qt][ks] = *(const bf16x8*)(qp + (size_t)(qw0 + qt * 16 + c) * QP + ks * 32 + g * 8);
;     const int kb_hi = q0 >> 6;
;     unsigned todo;
;     unsigned sel[2] = {0xffffffffu, 0xffffffffu};
;     unsigned selw = 0xffffffffu;
;     if (MODE == MODE_BSLC) {
;         sel[0] = selrow[qw0 + c]; sel[1] = selrow[qw0 + 16 + c];
;         unsigned u = sel[0] | sel[1];
; #pragma unroll
;         for (int off = 1; off < 64; off <<= 1) u |= __shfl_xor(u, off);
;         selw = __builtin_amdgcn_readfirstlane(u);
;         unsigned v = selrow[q0 + lane];
; #pragma unroll
;         for (int off = 1; off < 64; off <<= 1) v |= __shfl_xor(v, off);
;         todo = __builtin_amdgcn_readfirstlane(v) & (0xffffffffu >> (31 - kb_hi));
;     } else {
;         const int kb_lo = kb_hi >= 8 ? kb_hi - 8 : 0;
;         todo = (0xffffffffu >> (31 - kb_hi)) & (0xffffffffu << kb_lo);
;     }
;     __syncthreads();
;     if (tid < 512) { const int e = tid; lutw[e] = relb_b[(int)T5B[e & 127] * 16 + gk * 4 + (e >> 7)] * LOG2E; }
;     const float bias_far = relb_b[31 * 16 + h] * LOG2E;
; __global__ void __launch_bounds__(512, 2) mega_fwd(Args a) {
;     ...
;                 __syncthreads();
;                 if (threadIdx.x == 0) qslot[0] = atomicAdd(qctr, 1u);
;                 __syncthreads();
;                 const int it = (int)qslot[0];
;                 if (it >= 2048) break;
.LBB0_53:
	s_or_b64 exec, exec, s[0:1]
	v_readlane_b32 s0, v254, 48
	s_waitcnt lgkmcnt(0)
	s_barrier
	v_mov_b32_e32 v1, s0
	ds_read_b32 v1, v1
	s_movk_i32 s0, 0x7ff
	s_waitcnt lgkmcnt(0)
	v_cmp_lt_i32_e32 vcc, s0, v1
	v_readfirstlane_b32 s5, v1
	s_mov_b64 s[0:1], -1
	s_cbranch_vccnz .LBB0_48
	s_and_b32 s0, s5, 0xffffffc0
	s_bfe_u32 s19, s5, 0x50001
	s_and_b32 s4, s5, 1
	s_sub_i32 s36, 0x7c0, s0
	s_mul_i32 s0, s19, 0xe18000
	v_readlane_b32 s6, v252, 52
	v_readlane_b32 s7, v252, 53
	s_add_u32 s13, s6, s0
	s_addc_u32 s41, s7, 0
	s_lshl_b32 s40, s4, 2
	s_lshl_b32 s0, s19, 14
	v_readlane_b32 s1, v252, 14
	s_add_u32 s0, s1, s0
	v_readlane_b32 s1, v252, 15
	v_mov_b32_e32 v180, v214
	s_addc_u32 s1, s1, 0
	s_lshl_b32 s5, s4, 13
	v_mov_b32_e32 v10, v214
	s_add_u32 s0, s0, s5
	s_addc_u32 s1, s1, 0
	v_readfirstlane_b32 s5, v10
	s_bfe_u32 s7, s5, 0x20006
	s_or_b32 s8, s7, s40
	s_lshl_b32 s6, s8, 7
	s_add_u32 s10, s13, s6
	s_addc_u32 s11, s41, 0
	s_ashr_i32 s5, s5, 3
	s_and_b32 s6, s5, 0xffffffe0
	v_and_b32_e32 v1, 15, v10
	s_add_i32 s6, s6, s36
	v_or_b32_e32 v2, s6, v1
	v_ashrrev_i32_e32 v3, 31, v2
	v_lshl_add_u64 v[8:9], v[2:3], 2, s[0:1]
	v_and_or_b32 v12, v10, 63, s36
	v_mov_b32_e32 v13, v0
	v_lshl_add_u64 v[12:13], v[12:13], 2, s[0:1]
	global_load_dword v146, v[8:9], off
	global_load_dword v147, v[8:9], off offset:64
	global_load_dword v3, v[12:13], off
	v_mov_b32_e32 v9, v0
	v_and_b32_e32 v8, 48, v10
	v_lshl_add_u64 v[12:13], s[10:11], 0, v[8:9]
	v_or_b32_e32 v9, 16, v2
	v_mad_i64_i32 v[14:15], s[0:1], v2, s85, v[12:13]
	v_mad_i64_i32 v[12:13], s[0:1], v9, s85, v[12:13]
	global_load_dwordx4 v[40:43], v[14:15], off offset:1536
	global_load_dwordx4 v[44:47], v[14:15], off offset:1600
	global_load_dwordx4 v[48:51], v[12:13], off offset:1536
	global_load_dwordx4 v[52:55], v[12:13], off offset:1600
	v_cmp_lt_i32_e32 vcc, v219, v218
	s_barrier
	s_nop 0
	v_cndmask_b32_e32 v9, v217, v219, vcc
	v_lshlrev_b32_e32 v9, 2, v9
	v_cmp_lt_i32_e32 vcc, v220, v218
	s_waitcnt vmcnt(5)
	v_or_b32_e32 v11, v147, v146
	s_waitcnt vmcnt(4)
	ds_bpermute_b32 v12, v9, v3
	ds_bpermute_b32 v9, v9, v11
	v_cndmask_b32_e32 v13, v217, v220, vcc
	v_lshlrev_b32_e32 v13, 2, v13
	v_cmp_lt_i32_e32 vcc, v221, v218
	s_waitcnt lgkmcnt(1)
	v_or_b32_e32 v3, v12, v3
	s_waitcnt lgkmcnt(0)
	v_or_b32_e32 v9, v9, v11
	ds_bpermute_b32 v11, v13, v3
	ds_bpermute_b32 v12, v13, v9
	v_cndmask_b32_e32 v13, v217, v221, vcc
	v_lshlrev_b32_e32 v13, 2, v13
	v_cmp_lt_i32_e32 vcc, v222, v218
	s_waitcnt lgkmcnt(1)
	v_or_b32_e32 v3, v11, v3
	s_waitcnt lgkmcnt(0)
	v_or_b32_e32 v9, v12, v9
	ds_bpermute_b32 v11, v13, v3
	ds_bpermute_b32 v12, v13, v9
	v_cndmask_b32_e32 v13, v217, v222, vcc
	v_lshlrev_b32_e32 v13, 2, v13
	v_cmp_lt_i32_e32 vcc, v223, v218
	s_waitcnt lgkmcnt(1)
	v_or_b32_e32 v3, v11, v3
	s_waitcnt lgkmcnt(0)
	v_or_b32_e32 v9, v12, v9
	ds_bpermute_b32 v11, v13, v3
	ds_bpermute_b32 v12, v13, v9
	v_cndmask_b32_e32 v13, v217, v223, vcc
	v_lshlrev_b32_e32 v178, 2, v13
	v_cmp_lt_i32_e32 vcc, v224, v218
	s_waitcnt lgkmcnt(1)
	v_or_b32_e32 v3, v11, v3
	s_waitcnt lgkmcnt(0)
	v_or_b32_e32 v9, v12, v9
	ds_bpermute_b32 v11, v178, v3
	ds_bpermute_b32 v12, v178, v9
	v_cndmask_b32_e32 v13, v217, v224, vcc
	v_lshlrev_b32_e32 v179, 2, v13
	v_cmp_gt_i32_e32 vcc, s33, v10
	s_waitcnt lgkmcnt(1)
	v_or_b32_e32 v3, v11, v3
	s_waitcnt lgkmcnt(0)
	v_or_b32_e32 v9, v12, v9
	ds_bpermute_b32 v11, v179, v3
	ds_bpermute_b32 v12, v179, v9
	s_waitcnt lgkmcnt(1)
	v_or_b32_e32 v3, v11, v3
	s_waitcnt lgkmcnt(0)
	v_or_b32_e32 v9, v12, v9
	v_readfirstlane_b32 s9, v3
	v_readfirstlane_b32 s44, v9
	s_and_saveexec_b64 s[0:1], vcc
	s_cbranch_execz .LBB0_56
	v_and_b32_e32 v3, 0x7f, v10
	s_getpc_b64 s[10:11]
	s_add_u32 s10, s10, T5B@rel32@lo+4
	s_addc_u32 s11, s11, T5B@rel32@hi+12
	global_load_ubyte v3, v3, s[10:11]
	v_ashrrev_i32_e32 v9, 7, v10
	v_readlane_b32 s48, v255, 4
	v_readlane_b32 s52, v255, 8
	v_readlane_b32 s53, v255, 9
	v_readlane_b32 s49, v255, 5
	v_readlane_b32 s50, v255, 6
	v_readlane_b32 s51, v255, 7
	v_readlane_b32 s54, v255, 10
	v_readlane_b32 s55, v255, 11
	v_readlane_b32 s56, v255, 12
	v_readlane_b32 s57, v255, 13
	v_readlane_b32 s58, v255, 14
	v_readlane_b32 s59, v255, 15
	v_readlane_b32 s60, v255, 16
	v_readlane_b32 s61, v255, 17
	v_readlane_b32 s62, v255, 18
	v_readlane_b32 s63, v255, 19
	s_nop 1
	v_add_u32_e32 v228, 0x1f0, v9
	v_add_u32_e32 v228, s40, v228
	v_ashrrev_i32_e32 v229, 31, v228
	v_lshl_add_u64 v[228:229], v[228:229], 2, s[52:53]
	global_load_dword v230, v[228:229], off offset:32
	s_waitcnt vmcnt(0)
	v_lshlrev_b32_e32 v3, 4, v3
	v_add3_u32 v12, v9, s40, v3
	v_ashrrev_i32_e32 v13, 31, v12
	v_lshl_add_u64 v[12:13], v[12:13], 2, s[52:53]
	global_load_dword v3, v[12:13], off offset:32
	v_lshl_add_u32 v9, v10, 2, 0
	s_waitcnt vmcnt(0)
	v_mul_f32_e32 v3, 0x3fb8aa3b, v3
	ds_write_b32 v9, v3 offset:36864
	v_mul_f32_e32 v230, 0x3fb8aa3b, v230
	v_ashrrev_i32_e32 v231, 7, v10
	v_mul_u32_u24_e32 v231, 0xa00, v231
	v_and_b32_e32 v232, 0x7f, v10
	v_lshl_add_u32 v233, v232, 2, v231
	v_and_b32_e32 v234, 64, v10
	v_lshl_add_u32 v234, v234, 5, v233
	v_mov_b32_e32 v235, 0xf149f2ca
	ds_write_b32 v233, v3 offset:41216
	ds_write_b32 v234, v235 offset:40960
	ds_write_b32 v233, v230 offset:41728
	ds_write_b32 v233, v230 offset:42240
	ds_write_b32 v233, v230 offset:42752

; template <int MODE>
; __device__ __forceinline__ void attn_pass(LAS unsigned char* lds, const bf16_t* base, int gk, int q0, const float* relb_b, const unsigned* selrow, f32x4 (&o)[2][4]) {
;     ...
;                 const int dbase = selb ? (qw0 + 16 * qt + c - k0 - 4 * g) : -(1 << 22);
;                 float mx = -1e30f;
; #pragma unroll
;                 for (int nt = 0; nt < 4; ++nt)
; #pragma unroll
;                     for (int j = 0; j < 4; ++j) { const int dist = dbase - (16 * nt + j); const bool valid = (unsigned)dist < (unsigned)W;
;                         const unsigned di = (unsigned)dist < 127u ? (unsigned)dist : 127u;
;                         const float lg = valid ? (s[qt][nt][j] * C1 + lut[di]) : -1e30f; s[qt][nt][j] = lg; mx = fmaxf(mx, lg); }
;                 mx = fmaxf(mx, __shfl_xor(mx, 16)); mx = fmaxf(mx, __shfl_xor(mx, 32));
;                 mnew = fmaxf(mrun[qt], mx); alpha = __builtin_amdgcn_exp2f(mrun[qt] - mnew);
; #pragma unroll
;                 for (int nt = 0; nt < 4; ++nt)
; #pragma unroll
;                     for (int j = 0; j < 4; ++j) s[qt][nt][j] = __builtin_amdgcn_exp2f(s[qt][nt][j] - mnew);
.LBB0_75:
	v_cndmask_b32_e64 v3, v158, -1, s[0:1]
	s_mov_b32 s15, 0x100000
	v_add3_u32 v229, v3, s47, 16
	v_lshl_add_u32 v229, v229, 2, s47
	ds_read_b32 v112, v229 offset:41152
	ds_read_b32 v2, v229 offset:41148
	ds_read_b32 v114, v229 offset:41144
	ds_read_b32 v113, v229 offset:41140
	ds_read_b32 v115, v229 offset:41088
	ds_read_b32 v117, v229 offset:41084
	ds_read_b32 v118, v229 offset:41080
	ds_read_b32 v119, v229 offset:41076
	ds_read_b32 v120, v229 offset:41024
	ds_read_b32 v121, v229 offset:41020
	ds_read_b32 v122, v229 offset:41016
	ds_read_b32 v123, v229 offset:41012
	ds_read_b32 v124, v229 offset:40960
	ds_read_b32 v125, v229 offset:40956
	ds_read_b32 v126, v229 offset:40952
	ds_read_b32 v127, v229 offset:40948
	s_waitcnt lgkmcnt(0)
	v_fmac_f32_e32 v112, 0x3e38aa3b, v140
	v_fmac_f32_e32 v2, 0x3e38aa3b, v141
	v_fmac_f32_e32 v114, 0x3e38aa3b, v142
	v_fmac_f32_e32 v113, 0x3e38aa3b, v143
	v_fmac_f32_e32 v115, 0x3e38aa3b, v136
	v_fmac_f32_e32 v117, 0x3e38aa3b, v137
	v_fmac_f32_e32 v118, 0x3e38aa3b, v138
	v_fmac_f32_e32 v119, 0x3e38aa3b, v139
	v_fmac_f32_e32 v120, 0x3e38aa3b, v132
	v_fmac_f32_e32 v121, 0x3e38aa3b, v133
	v_fmac_f32_e32 v122, 0x3e38aa3b, v134
	v_fmac_f32_e32 v123, 0x3e38aa3b, v135
	v_fmac_f32_e32 v124, 0x3e38aa3b, v128
	v_fmac_f32_e32 v125, 0x3e38aa3b, v129
	v_fmac_f32_e32 v126, 0x3e38aa3b, v130
	v_fmac_f32_e32 v127, 0x3e38aa3b, v131
	v_max3_f32 v3, v112, s86, v2
	v_max3_f32 v3, v3, v114, v113
	v_max3_f32 v3, v3, v115, v117
	v_max3_f32 v3, v3, v118, v119
	v_max3_f32 v3, v3, v120, v121
	v_max3_f32 v3, v3, v122, v123
	v_max3_f32 v3, v3, v124, v125
	v_max3_f32 v3, v3, v126, v127
	v_mov_b32_e32 v116, v3
	s_waitcnt lgkmcnt(0)
	s_nop 1
	v_permlane16_swap_b32_e32 v3, v116
	s_nop 0
	v_max_f32_e32 v3, v3, v116
	v_mov_b32_e32 v116, v3
	s_nop 1
	v_permlane32_swap_b32_e32 v3, v116
	s_nop 0
	v_max3_f32 v3, v157, v3, v116
	v_sub_f32_e32 v2, v2, v3
	v_sub_f32_e32 v116, v113, v3
	v_exp_f32_e32 v113, v2
	v_sub_f32_e32 v2, v117, v3
	v_exp_f32_e32 v117, v2
	v_sub_f32_e32 v2, v118, v3
	v_exp_f32_e32 v118, v2
	v_sub_f32_e32 v2, v119, v3
	v_exp_f32_e32 v119, v2
	v_sub_f32_e32 v2, v120, v3
	v_exp_f32_e32 v120, v2
	v_sub_f32_e32 v2, v121, v3
	v_exp_f32_e32 v121, v2
	v_sub_f32_e32 v2, v122, v3
	v_exp_f32_e32 v122, v2
	v_sub_f32_e32 v2, v123, v3
	v_exp_f32_e32 v123, v2
	v_sub_f32_e32 v2, v124, v3
	v_exp_f32_e32 v124, v2
	v_sub_f32_e32 v2, v125, v3
	v_sub_f32_e32 v112, v112, v3
	v_sub_f32_e32 v114, v114, v3
	v_sub_f32_e32 v156, v115, v3
	v_exp_f32_e32 v125, v2
	v_sub_f32_e32 v2, v126, v3
	v_exp_f32_e32 v112, v112
	v_exp_f32_e32 v114, v114
	v_exp_f32_e32 v115, v116
	v_exp_f32_e32 v116, v156
	v_exp_f32_e32 v126, v2
	v_sub_f32_e32 v156, v127, v3
	s_branch .LBB0_65

; template <int MODE>
; __device__ __forceinline__ void attn_pass(LAS unsigned char* lds, const bf16_t* base, int gk, int q0, const float* relb_b, const unsigned* selrow, f32x4 (&o)[2][4]) {
;     ...
;                 const int dbase = selb ? (qw0 + 16 * qt + c - k0 - 4 * g) : -(1 << 22);
;                 float mx = -1e30f;
; #pragma unroll
;                 for (int nt = 0; nt < 4; ++nt)
; #pragma unroll
;                     for (int j = 0; j < 4; ++j) { const int dist = dbase - (16 * nt + j); const bool valid = (unsigned)dist < (unsigned)W;
;                         const unsigned di = (unsigned)dist < 127u ? (unsigned)dist : 127u;
;                         const float lg = valid ? (s[qt][nt][j] * C1 + lut[di]) : -1e30f; s[qt][nt][j] = lg; mx = fmaxf(mx, lg); }
;                 mx = fmaxf(mx, __shfl_xor(mx, 16)); mx = fmaxf(mx, __shfl_xor(mx, 32));
;                 mnew = fmaxf(mrun[qt], mx); alpha = __builtin_amdgcn_exp2f(mrun[qt] - mnew);
; #pragma unroll
;                 for (int nt = 0; nt < 4; ++nt)
; #pragma unroll
;                     for (int j = 0; j < 4; ++j) s[qt][nt][j] = __builtin_amdgcn_exp2f(s[qt][nt][j] - mnew);
.LBB0_109:
	v_add_u32_e32 v127, 16, v158
	v_cndmask_b32_e64 v127, v127, -1, s[0:1]
	s_mov_b32 s10, 0x100000
	v_add3_u32 v229, v127, s47, 16
	v_lshl_add_u32 v229, v229, 2, s47
	ds_read_b32 v129, v229 offset:41152
	ds_read_b32 v128, v229 offset:41148
	ds_read_b32 v131, v229 offset:41144
	ds_read_b32 v130, v229 offset:41140
	ds_read_b32 v132, v229 offset:41088
	ds_read_b32 v133, v229 offset:41084
	ds_read_b32 v134, v229 offset:41080
	ds_read_b32 v135, v229 offset:41076
	ds_read_b32 v136, v229 offset:41024
	ds_read_b32 v137, v229 offset:41020
	ds_read_b32 v138, v229 offset:41016
	ds_read_b32 v139, v229 offset:41012
	ds_read_b32 v140, v229 offset:40960
	ds_read_b32 v141, v229 offset:40956
	ds_read_b32 v142, v229 offset:40952
	ds_read_b32 v143, v229 offset:40948
	s_waitcnt lgkmcnt(0)
	v_fmac_f32_e32 v129, 0x3e38aa3b, v108
	v_fmac_f32_e32 v128, 0x3e38aa3b, v109
	v_fmac_f32_e32 v131, 0x3e38aa3b, v110
	v_fmac_f32_e32 v130, 0x3e38aa3b, v111
	v_fmac_f32_e32 v132, 0x3e38aa3b, v104
	v_fmac_f32_e32 v133, 0x3e38aa3b, v105
	v_fmac_f32_e32 v134, 0x3e38aa3b, v106
	v_fmac_f32_e32 v135, 0x3e38aa3b, v107
	v_fmac_f32_e32 v136, 0x3e38aa3b, v100
	v_fmac_f32_e32 v137, 0x3e38aa3b, v101
	v_fmac_f32_e32 v138, 0x3e38aa3b, v102
	v_fmac_f32_e32 v139, 0x3e38aa3b, v103
	v_fmac_f32_e32 v140, 0x3e38aa3b, v96
	v_fmac_f32_e32 v141, 0x3e38aa3b, v97
	v_fmac_f32_e32 v142, 0x3e38aa3b, v98
	v_fmac_f32_e32 v143, 0x3e38aa3b, v99
	v_max3_f32 v127, v129, s86, v128
	v_max3_f32 v127, v127, v131, v130
	v_max3_f32 v127, v127, v132, v133
	v_max3_f32 v127, v127, v134, v135
	v_max3_f32 v127, v127, v136, v137
	v_max3_f32 v127, v127, v138, v139
	v_max3_f32 v127, v127, v140, v141
	v_max3_f32 v127, v127, v142, v143
	v_mov_b32_e32 v157, v127
	s_waitcnt lgkmcnt(0)
	s_nop 1
	v_permlane16_swap_b32_e32 v127, v157
	s_nop 0
	v_max_f32_e32 v127, v127, v157
	v_mov_b32_e32 v157, v127
	s_nop 1
	v_permlane32_swap_b32_e32 v127, v157
	s_nop 0
	v_max3_f32 v127, v155, v127, v157
	v_sub_f32_e32 v129, v129, v127
	v_sub_f32_e32 v157, v128, v127
	v_sub_f32_e32 v131, v131, v127
	v_sub_f32_e32 v158, v130, v127
	v_sub_f32_e32 v132, v132, v127
	v_sub_f32_e32 v133, v133, v127
	v_sub_f32_e32 v134, v134, v127
	v_sub_f32_e32 v135, v135, v127
	v_sub_f32_e32 v136, v136, v127
	v_sub_f32_e32 v137, v137, v127
	v_sub_f32_e32 v138, v138, v127
	v_sub_f32_e32 v139, v139, v127
	v_sub_f32_e32 v140, v140, v127
	v_sub_f32_e32 v141, v141, v127
	v_sub_f32_e32 v142, v142, v127
	v_exp_f32_e32 v128, v129
	v_exp_f32_e32 v129, v157
	v_exp_f32_e32 v130, v131
	v_exp_f32_e32 v131, v158
	v_exp_f32_e32 v132, v132
	v_exp_f32_e32 v133, v133
	v_exp_f32_e32 v134, v134
	v_exp_f32_e32 v135, v135
	v_exp_f32_e32 v136, v136
	v_exp_f32_e32 v137, v137
	v_exp_f32_e32 v138, v138
	v_exp_f32_e32 v139, v139
	v_exp_f32_e32 v140, v140
	v_exp_f32_e32 v141, v141
	v_exp_f32_e32 v142, v142
	v_sub_f32_e32 v157, v143, v127
	s_branch .LBB0_69

; template <int MODE>
; __device__ __forceinline__ void attn_pass(LAS unsigned char* lds, const bf16_t* base, int gk, int q0, const float* relb_b, const unsigned* selrow, f32x4 (&o)[2][4]) {
;     ...
;                 const int dbase = selb ? (qw0 + 16 * qt + c - k0 - 4 * g) : -(1 << 22);
;                 float mx = -1e30f;
; #pragma unroll
;                 for (int nt = 0; nt < 4; ++nt)
; #pragma unroll
;                     for (int j = 0; j < 4; ++j) { const int dist = dbase - (16 * nt + j); const bool valid = (unsigned)dist < (unsigned)W;
;                         const unsigned di = (unsigned)dist < 127u ? (unsigned)dist : 127u;
;                         const float lg = valid ? (s[qt][nt][j] * C1 + lut[di]) : -1e30f; s[qt][nt][j] = lg; mx = fmaxf(mx, lg); }
;                 mx = fmaxf(mx, __shfl_xor(mx, 16)); mx = fmaxf(mx, __shfl_xor(mx, 32));
;                 mnew = fmaxf(mrun[qt], mx); alpha = __builtin_amdgcn_exp2f(mrun[qt] - mnew);
; #pragma unroll
;                 for (int nt = 0; nt < 4; ++nt)
; #pragma unroll
;                     for (int j = 0; j < 4; ++j) s[qt][nt][j] = __builtin_amdgcn_exp2f(s[qt][nt][j] - mnew);
.LBB0_161:
	v_add3_u32 v229, v198, s42, 16
	v_lshl_add_u32 v229, v229, 2, s42
	ds_read_b32 v144, v229 offset:41152
	ds_read_b32 v2, v229 offset:41148
	ds_read_b32 v146, v229 offset:41144
	ds_read_b32 v145, v229 offset:41140
	ds_read_b32 v147, v229 offset:41088
	ds_read_b32 v149, v229 offset:41084
	ds_read_b32 v152, v229 offset:41080
	ds_read_b32 v151, v229 offset:41076
	ds_read_b32 v154, v229 offset:41024
	ds_read_b32 v153, v229 offset:41020
	ds_read_b32 v156, v229 offset:41016
	ds_read_b32 v155, v229 offset:41012
	ds_read_b32 v158, v229 offset:40960
	ds_read_b32 v157, v229 offset:40956
	ds_read_b32 v197, v229 offset:40952
	ds_read_b32 v159, v229 offset:40948
	s_waitcnt lgkmcnt(0)
	v_fmac_f32_e32 v144, 0x3e38aa3b, v172
	v_fmac_f32_e32 v2, 0x3e38aa3b, v173
	v_fmac_f32_e32 v146, 0x3e38aa3b, v174
	v_fmac_f32_e32 v145, 0x3e38aa3b, v175
	v_fmac_f32_e32 v147, 0x3e38aa3b, v168
	v_fmac_f32_e32 v149, 0x3e38aa3b, v169
	v_fmac_f32_e32 v152, 0x3e38aa3b, v170
	v_fmac_f32_e32 v151, 0x3e38aa3b, v171
	v_fmac_f32_e32 v154, 0x3e38aa3b, v164
	v_fmac_f32_e32 v153, 0x3e38aa3b, v165
	v_fmac_f32_e32 v156, 0x3e38aa3b, v166
	v_fmac_f32_e32 v155, 0x3e38aa3b, v167
	v_fmac_f32_e32 v158, 0x3e38aa3b, v160
	v_fmac_f32_e32 v157, 0x3e38aa3b, v161
	v_fmac_f32_e32 v197, 0x3e38aa3b, v162
	v_fmac_f32_e32 v159, 0x3e38aa3b, v163
	v_max3_f32 v3, v144, s86, v2
	v_max3_f32 v3, v3, v146, v145
	v_max3_f32 v3, v3, v147, v149
	v_max3_f32 v3, v3, v152, v151
	v_max3_f32 v3, v3, v154, v153
	v_max3_f32 v3, v3, v156, v155
	v_max3_f32 v3, v3, v158, v157
	v_max3_f32 v3, v3, v197, v159
	v_mov_b32_e32 v148, v3
	s_waitcnt lgkmcnt(0)
	s_nop 1
	v_permlane16_swap_b32_e32 v3, v148
	s_nop 0
	v_max_f32_e32 v3, v3, v148
	v_mov_b32_e32 v148, v3
	s_nop 1
	v_permlane32_swap_b32_e32 v3, v148
	s_nop 0
	v_max3_f32 v3, v200, v3, v148
	v_sub_f32_e32 v2, v2, v3
	v_sub_f32_e32 v148, v145, v3
	v_exp_f32_e32 v145, v2
	v_sub_f32_e32 v2, v149, v3
	v_sub_f32_e32 v150, v147, v3
	v_exp_f32_e32 v149, v2
	v_sub_f32_e32 v2, v152, v3
	v_exp_f32_e32 v147, v148
	v_exp_f32_e32 v148, v150
	v_exp_f32_e32 v150, v2
	v_sub_f32_e32 v2, v151, v3
	v_exp_f32_e32 v151, v2
	v_sub_f32_e32 v2, v154, v3
	v_exp_f32_e32 v152, v2
	v_sub_f32_e32 v2, v153, v3
	v_exp_f32_e32 v153, v2
	v_sub_f32_e32 v2, v156, v3
	v_exp_f32_e32 v154, v2
	v_sub_f32_e32 v2, v155, v3
	v_exp_f32_e32 v155, v2
	v_sub_f32_e32 v2, v158, v3
	v_exp_f32_e32 v156, v2
	v_sub_f32_e32 v2, v157, v3
	v_sub_f32_e32 v144, v144, v3
	v_sub_f32_e32 v146, v146, v3
	v_exp_f32_e32 v157, v2
	v_sub_f32_e32 v2, v197, v3
	v_exp_f32_e32 v144, v144
	v_exp_f32_e32 v146, v146
	v_exp_f32_e32 v158, v2
	v_sub_f32_e32 v197, v159, v3
	s_branch .LBB0_153

; template <int MODE>
; __device__ __forceinline__ void attn_pass(LAS unsigned char* lds, const bf16_t* base, int gk, int q0, const float* relb_b, const unsigned* selrow, f32x4 (&o)[2][4]) {
;     ...
;                 const int dbase = selb ? (qw0 + 16 * qt + c - k0 - 4 * g) : -(1 << 22);
;                 float mx = -1e30f;
; #pragma unroll
;                 for (int nt = 0; nt < 4; ++nt)
; #pragma unroll
;                     for (int j = 0; j < 4; ++j) { const int dist = dbase - (16 * nt + j); const bool valid = (unsigned)dist < (unsigned)W;
;                         const unsigned di = (unsigned)dist < 127u ? (unsigned)dist : 127u;
;                         const float lg = valid ? (s[qt][nt][j] * C1 + lut[di]) : -1e30f; s[qt][nt][j] = lg; mx = fmaxf(mx, lg); }
;                 mx = fmaxf(mx, __shfl_xor(mx, 16)); mx = fmaxf(mx, __shfl_xor(mx, 32));
;                 mnew = fmaxf(mrun[qt], mx); alpha = __builtin_amdgcn_exp2f(mrun[qt] - mnew);
; #pragma unroll
;                 for (int nt = 0; nt < 4; ++nt)
; #pragma unroll
;                     for (int j = 0; j < 4; ++j) s[qt][nt][j] = __builtin_amdgcn_exp2f(s[qt][nt][j] - mnew);
.LBB0_195:
	v_or_b32_e32 v159, 16, v199
	v_sub_u32_e32 v228, v159, v189
	v_add3_u32 v229, v228, s42, 16
	v_lshl_add_u32 v229, v229, 2, s42
	ds_read_b32 v161, v229 offset:41152
	ds_read_b32 v160, v229 offset:41148
	ds_read_b32 v163, v229 offset:41144
	ds_read_b32 v162, v229 offset:41140
	ds_read_b32 v164, v229 offset:41088
	ds_read_b32 v165, v229 offset:41084
	ds_read_b32 v166, v229 offset:41080
	ds_read_b32 v167, v229 offset:41076
	ds_read_b32 v168, v229 offset:41024
	ds_read_b32 v169, v229 offset:41020
	ds_read_b32 v170, v229 offset:41016
	ds_read_b32 v171, v229 offset:41012
	ds_read_b32 v175, v229 offset:40960
	ds_read_b32 v174, v229 offset:40956
	ds_read_b32 v199, v229 offset:40952
	ds_read_b32 v198, v229 offset:40948
	s_waitcnt lgkmcnt(0)
	v_fmac_f32_e32 v161, 0x3e38aa3b, v140
	v_fmac_f32_e32 v160, 0x3e38aa3b, v141
	v_fmac_f32_e32 v163, 0x3e38aa3b, v142
	v_fmac_f32_e32 v162, 0x3e38aa3b, v143
	v_fmac_f32_e32 v164, 0x3e38aa3b, v136
	v_fmac_f32_e32 v165, 0x3e38aa3b, v137
	v_fmac_f32_e32 v166, 0x3e38aa3b, v138
	v_fmac_f32_e32 v167, 0x3e38aa3b, v139
	v_fmac_f32_e32 v168, 0x3e38aa3b, v132
	v_fmac_f32_e32 v169, 0x3e38aa3b, v133
	v_fmac_f32_e32 v170, 0x3e38aa3b, v134
	v_fmac_f32_e32 v171, 0x3e38aa3b, v135
	v_fmac_f32_e32 v175, 0x3e38aa3b, v128
	v_fmac_f32_e32 v174, 0x3e38aa3b, v129
	v_fmac_f32_e32 v199, 0x3e38aa3b, v130
	v_fmac_f32_e32 v198, 0x3e38aa3b, v131
	v_max3_f32 v159, v161, s86, v160
	v_max3_f32 v159, v159, v163, v162
	v_max3_f32 v159, v159, v164, v165
	v_max3_f32 v159, v159, v166, v167
	v_max3_f32 v159, v159, v168, v169
	v_max3_f32 v159, v159, v170, v171
	v_max3_f32 v159, v159, v175, v174
	v_max3_f32 v159, v159, v199, v198
	v_mov_b32_e32 v172, v159
	s_waitcnt lgkmcnt(0)
	s_nop 1
	v_permlane16_swap_b32_e32 v159, v172
	s_nop 0
	v_max_f32_e32 v159, v159, v172
	v_mov_b32_e32 v172, v159
	s_nop 1
	v_permlane32_swap_b32_e32 v159, v172
	s_nop 0
	v_max3_f32 v159, v196, v159, v172
	v_sub_f32_e32 v161, v161, v159
	v_sub_f32_e32 v172, v160, v159
	v_sub_f32_e32 v163, v163, v159
	v_sub_f32_e32 v173, v162, v159
	v_sub_f32_e32 v164, v164, v159
	v_exp_f32_e32 v160, v161
	v_exp_f32_e32 v161, v172
	v_exp_f32_e32 v162, v163
	v_exp_f32_e32 v163, v173
	v_sub_f32_e32 v165, v165, v159
	v_sub_f32_e32 v166, v166, v159
	v_sub_f32_e32 v167, v167, v159
	v_sub_f32_e32 v168, v168, v159
	v_sub_f32_e32 v169, v169, v159
	v_sub_f32_e32 v170, v170, v159
	v_sub_f32_e32 v171, v171, v159
	v_sub_f32_e32 v172, v175, v159
	v_sub_f32_e32 v173, v174, v159
	v_sub_f32_e32 v174, v199, v159
	v_exp_f32_e32 v164, v164
	v_exp_f32_e32 v165, v165
	v_exp_f32_e32 v166, v166
	v_exp_f32_e32 v167, v167
	v_exp_f32_e32 v168, v168
	v_exp_f32_e32 v169, v169
	v_exp_f32_e32 v170, v170
	v_exp_f32_e32 v171, v171
	v_exp_f32_e32 v172, v172
	v_exp_f32_e32 v173, v173
	v_exp_f32_e32 v174, v174
	v_sub_f32_e32 v200, v198, v159
	s_branch .LBB0_157
